# speedup vs baseline: 1.0446x; 1.0005x over previous
.Lml_w2:
	s_waitcnt vmcnt(3)
	s_barrier
	s_add_i32 s7, s7, 1
	s_add_i32 s14, s21, s7
	v_add_f32_e32 v185, v185, v154
	v_lshl_add_u64 v[156:157], v[156:157], 0, s[94:95]
	v_lshl_add_u64 v[158:159], v[158:159], 0, s[94:95]
	s_cmp_lg_u32 s14, 4
	v_lshl_add_u64 v[172:173], v[172:173], 0, s[94:95]
	s_cbranch_scc1 .LBB0_680
	s_branch .LBB0_694

.Lml_pk2:
	v_mfma_f32_32x32x16_bf16 v[16:31], v[132:135], v[32:35], v[16:31]
	v_mfma_f32_32x32x16_bf16 v[0:15], v[136:139], v[36:39], v[0:15]
	v_mfma_f32_32x32x16_bf16 v[16:31], v[128:131], v[36:39], v[16:31]
	s_cbranch_vccnz .Lml_lastwait
	s_and_b64 vcc, exec, s[2:3]
	s_cbranch_vccz .Lml_w2
	s_waitcnt vmcnt(2)
